# removed the conservative full vmcnt(0) drain at the tile start of the out-odd, up and down GEMM loops (the counted in-loop waits already cover the staged tiles); on top of the up-GEMM load-segment rec
# speedup vs baseline: 1.0058x; 1.0058x over previous
; #define PG8_STAGE(bufoff, gbase, voff) do { _Pragma("unroll") for (int _i = 0; _i < 2; ++_i) \
;         __builtin_amdgcn_global_load_lds((const unsigned*)((const char*)(gbase) + (voff)[_i]), (LAS unsigned*)(lds + (bufoff) + ldsw + _i * 8192), 16, 0, 0); } while (0)
; #define PG8_LDA(dst, b, h) do { _Pragma("unroll") for (int m = 0; m < 4; ++m) _Pragma("unroll") for (int k = 0; k < 2; ++k) dst[m][k] = *(const LAS bf16x8*)(lds + PG8_SA(b, h) + aoff + m * 2048 + k * 1024); } while (0)
; #define PG8_LDB(dst, b, h) do { _Pragma("unroll") for (int n = 0; n < 2; ++n) _Pragma("unroll") for (int k = 0; k < 2; ++k) dst[n][k] = *(const LAS bf16x8*)(lds + PG8_SB(b, h) + boff + n * 2048 + k * 1024); } while (0)
; #define PG8_MMA(ai, bj, At, Bt) do { __builtin_amdgcn_s_setprio(1); _Pragma("unroll") for (int m = 0; m < 4; ++m) _Pragma("unroll") for (int n = 0; n < 2; ++n) _Pragma("unroll") for (int k = 0; k < 2; ++k) \
;         acc[ai][bj][m][n] = __builtin_amdgcn_mfma_f32_16x16x32_bf16(Bt[n][k], At[m][k], acc[ai][bj][m][n], 0, 0, 0); __builtin_amdgcn_s_setprio(0); } while (0)
; #define PG8_WAIT_V(n) asm volatile("s_waitcnt vmcnt(" #n ")" ::: "memory")
; #define PG8_WAIT_L(n) asm volatile("s_waitcnt lgkmcnt(" #n ")" ::: "memory")
; #define PG8_BAR __builtin_amdgcn_s_barrier()
; #define PG8_SCHED __builtin_amdgcn_sched_barrier(0)
; template <class Epi, class Sched, bool ALIGN_EPI = false, bool SP2 = false>
; __device__ __forceinline__ void gemm_phase(LAS unsigned char* lds, const Gemm g, const Sched& S, const Epi& E, int wid) {
;     ...
;             PG8_LDB(B0, 0, 0); PG8_LDB(B1, 0, 1); PG8_SCHED; PG8_LDA(At, 0, 0); PG8_STAGE(PG8_SA(1, 1), a1 + hstepA, voffA);
;             PG8_WAIT_V(8); PG8_WAIT_L(0); PG8_BAR; PG8_MMA(0, 0, At, B0); PG8_MMA(0, 1, At, B1); PG8_BAR; PG8_SCHED;
;     ...
; #pragma unroll
;         for (int a = 0; a < 2; ++a)
; #pragma unroll
;             for (int b = 0; b < 2; ++b)
; #pragma unroll
;                 for (int m = 0; m < 4; ++m)
; #pragma unroll
;                     for (int n = 0; n < 2; ++n) acc[a][b][m][n] = (f32x4){0.f, 0.f, 0.f, 0.f};
;         cur = nxt; cA = nA; cB = nB; ++ui;
.LBB0_880:
	s_ashr_i32 s31, s30, 31
	s_lshl_b64 s[34:35], s[30:31], 20
	s_add_u32 s34, s6, s34
	s_addc_u32 s35, s7, s35
	s_and_b64 s[38:39], s[10:11], exec
	s_cselect_b32 s31, s35, s41
	s_cselect_b32 s54, s34, s40
	s_ashr_i32 s29, s28, 31
	s_lshl_b64 s[38:39], s[28:29], 20
	s_add_u32 s38, s4, s38
	s_addc_u32 s39, s5, s39
	s_and_b64 s[46:47], s[10:11], exec
	s_cselect_b32 s29, s39, s45
	s_cselect_b32 s55, s38, s44
	s_add_u32 s40, s40, 0x80080
	s_addc_u32 s41, s41, 0
	s_add_u32 s56, s44, 0x100
	v_mov_b32_e32 v0, 0
	s_addc_u32 s57, s45, 0
	s_mov_b32 s58, -2
	v_mov_b32_e32 v1, v0
	v_mov_b32_e32 v2, v0
	v_mov_b32_e32 v3, v0
	v_mov_b32_e32 v4, v0
	v_mov_b32_e32 v5, v0
	v_mov_b32_e32 v6, v0
	v_mov_b32_e32 v7, v0
	v_mov_b32_e32 v16, v0
	v_mov_b32_e32 v17, v0
	v_mov_b32_e32 v18, v0
	v_mov_b32_e32 v19, v0
	v_mov_b32_e32 v20, v0
	v_mov_b32_e32 v21, v0
	v_mov_b32_e32 v22, v0
	v_mov_b32_e32 v23, v0
	v_mov_b32_e32 v32, v0
	v_mov_b32_e32 v33, v0
	v_mov_b32_e32 v34, v0
	v_mov_b32_e32 v35, v0
	v_mov_b32_e32 v36, v0
	v_mov_b32_e32 v37, v0
	v_mov_b32_e32 v38, v0
	v_mov_b32_e32 v39, v0
	v_mov_b32_e32 v48, v0
	v_mov_b32_e32 v49, v0
	v_mov_b32_e32 v50, v0
	v_mov_b32_e32 v51, v0
	v_mov_b32_e32 v52, v0
	v_mov_b32_e32 v53, v0
	v_mov_b32_e32 v54, v0
	v_mov_b32_e32 v55, v0
	v_mov_b32_e32 v8, v0
	v_mov_b32_e32 v9, v0
	v_mov_b32_e32 v10, v0
	v_mov_b32_e32 v11, v0
	v_mov_b32_e32 v12, v0
	v_mov_b32_e32 v13, v0
	v_mov_b32_e32 v14, v0
	v_mov_b32_e32 v15, v0
	v_mov_b32_e32 v24, v0
	v_mov_b32_e32 v25, v0
	v_mov_b32_e32 v26, v0
	v_mov_b32_e32 v27, v0
	v_mov_b32_e32 v28, v0
	v_mov_b32_e32 v29, v0
	v_mov_b32_e32 v30, v0
	v_mov_b32_e32 v31, v0
	v_mov_b32_e32 v40, v0
	v_mov_b32_e32 v41, v0
	v_mov_b32_e32 v42, v0
	v_mov_b32_e32 v43, v0
	v_mov_b32_e32 v44, v0
	v_mov_b32_e32 v45, v0
	v_mov_b32_e32 v46, v0
	v_mov_b32_e32 v47, v0
	v_mov_b32_e32 v56, v0
	v_mov_b32_e32 v57, v0
	v_mov_b32_e32 v58, v0
	v_mov_b32_e32 v59, v0
	v_mov_b32_e32 v60, v0
	v_mov_b32_e32 v61, v0
	v_mov_b32_e32 v62, v0
	v_mov_b32_e32 v63, v0
	v_mov_b32_e32 v64, v0
	v_mov_b32_e32 v65, v0
	v_mov_b32_e32 v66, v0
	v_mov_b32_e32 v67, v0
	v_mov_b32_e32 v68, v0
	v_mov_b32_e32 v69, v0
	v_mov_b32_e32 v70, v0
	v_mov_b32_e32 v71, v0
	v_mov_b32_e32 v80, v0
	v_mov_b32_e32 v81, v0
	v_mov_b32_e32 v82, v0
	v_mov_b32_e32 v83, v0
	v_mov_b32_e32 v84, v0
	v_mov_b32_e32 v85, v0
	v_mov_b32_e32 v86, v0
	v_mov_b32_e32 v87, v0
	v_mov_b32_e32 v96, v0
	v_mov_b32_e32 v97, v0
	v_mov_b32_e32 v98, v0
	v_mov_b32_e32 v99, v0
	v_mov_b32_e32 v100, v0
	v_mov_b32_e32 v101, v0
	v_mov_b32_e32 v102, v0
	v_mov_b32_e32 v103, v0
	v_mov_b32_e32 v112, v0
	v_mov_b32_e32 v113, v0
	v_mov_b32_e32 v114, v0
	v_mov_b32_e32 v115, v0
	v_mov_b32_e32 v116, v0
	v_mov_b32_e32 v117, v0
	v_mov_b32_e32 v118, v0
	v_mov_b32_e32 v119, v0
	v_mov_b32_e32 v72, v0
	v_mov_b32_e32 v73, v0
	v_mov_b32_e32 v74, v0
	v_mov_b32_e32 v75, v0
	v_mov_b32_e32 v76, v0
	v_mov_b32_e32 v77, v0
	v_mov_b32_e32 v78, v0
	v_mov_b32_e32 v79, v0
	v_mov_b32_e32 v88, v0
	v_mov_b32_e32 v89, v0
	v_mov_b32_e32 v90, v0
	v_mov_b32_e32 v91, v0
	v_mov_b32_e32 v92, v0
	v_mov_b32_e32 v93, v0
	v_mov_b32_e32 v94, v0
	v_mov_b32_e32 v95, v0
	v_mov_b32_e32 v104, v0
	v_mov_b32_e32 v105, v0
	v_mov_b32_e32 v106, v0
	v_mov_b32_e32 v107, v0
	v_mov_b32_e32 v108, v0
	v_mov_b32_e32 v109, v0
	v_mov_b32_e32 v110, v0
	v_mov_b32_e32 v111, v0
	v_mov_b32_e32 v120, v0
	v_mov_b32_e32 v121, v0
	v_mov_b32_e32 v122, v0
	v_mov_b32_e32 v123, v0
	v_mov_b32_e32 v124, v0
	v_mov_b32_e32 v125, v0
	v_mov_b32_e32 v126, v0
	v_mov_b32_e32 v127, v0
.LBB0_881:
	s_add_u32 s44, s40, 0xfff80080
	s_addc_u32 s45, s41, -1
	s_add_i32 s59, 0, 0x10000
	s_cmp_eq_u32 s58, 28
	s_cselect_b32 s47, s31, s45
	s_cselect_b32 s46, s54, s44
	s_cselect_b32 s45, s29, s57
	s_cselect_b32 s44, s55, s56
	s_add_i32 s66, 0, 0x14000
	v_add_u32_e32 v140, s59, v189
	v_add_u32_e32 v166, s66, v189
	ds_read_b128 v[128:131], v140
	ds_read_b128 v[132:135], v140 offset:1024
	ds_read_b128 v[136:139], v140 offset:2048
	ds_read_b128 v[140:143], v140 offset:3072
	ds_read_b128 v[144:147], v166
	ds_read_b128 v[148:151], v166 offset:1024
	ds_read_b128 v[152:155], v166 offset:2048
	ds_read_b128 v[166:169], v166 offset:3072
	v_lshl_add_u64 v[186:187], s[40:41], 0, v[162:163]
	s_add_i32 m0, s36, 0xc000
	ds_read_b128 v[170:173], v191
	ds_read_b128 v[174:177], v191 offset:1024
	ds_read_b128 v[178:181], v191 offset:2048
	ds_read_b128 v[182:185], v191 offset:3072
	ds_read_b128 v[200:203], v191 offset:4096
	ds_read_b128 v[204:207], v191 offset:5120
	ds_read_b128 v[208:211], v191 offset:6144
	ds_read_b128 v[212:215], v191 offset:7168
	global_load_lds_dwordx4 v[186:187], off
	v_lshl_add_u64 v[186:187], s[40:41], 0, v[164:165]
	s_add_i32 m0, s36, 0xe000
	s_nop 0
	global_load_lds_dwordx4 v[186:187], off
	s_waitcnt vmcnt(8)
	s_waitcnt lgkmcnt(0)
	s_barrier
; #define PG8_STAGE(bufoff, gbase, voff) do { _Pragma("unroll") for (int _i = 0; _i < 2; ++_i) \
;         __builtin_amdgcn_global_load_lds((const unsigned*)((const char*)(gbase) + (voff)[_i]), (LAS unsigned*)(lds + (bufoff) + ldsw + _i * 8192), 16, 0, 0); } while (0)
; #define PG8_LDA(dst, b, h) do { _Pragma("unroll") for (int m = 0; m < 4; ++m) _Pragma("unroll") for (int k = 0; k < 2; ++k) dst[m][k] = *(const LAS bf16x8*)(lds + PG8_SA(b, h) + aoff + m * 2048 + k * 1024); } while (0)
; #define PG8_MMA(ai, bj, At, Bt) do { __builtin_amdgcn_s_setprio(1); _Pragma("unroll") for (int m = 0; m < 4; ++m) _Pragma("unroll") for (int n = 0; n < 2; ++n) _Pragma("unroll") for (int k = 0; k < 2; ++k) \
;         acc[ai][bj][m][n] = __builtin_amdgcn_mfma_f32_16x16x32_bf16(Bt[n][k], At[m][k], acc[ai][bj][m][n], 0, 0, 0); __builtin_amdgcn_s_setprio(0); } while (0)
; #define PG8_WAIT_V(n) asm volatile("s_waitcnt vmcnt(" #n ")" ::: "memory")
; #define PG8_WAIT_L(n) asm volatile("s_waitcnt lgkmcnt(" #n ")" ::: "memory")
; #define PG8_BAR __builtin_amdgcn_s_barrier()
; #define PG8_SCHED __builtin_amdgcn_sched_barrier(0)
; template <class Epi, class Sched, bool ALIGN_EPI = false, bool SP2 = false>
; __device__ __forceinline__ void gemm_phase(LAS unsigned char* lds, const Gemm g, const Sched& S, const Epi& E, int wid) {
;     ...
;             PG8_WAIT_V(8); PG8_WAIT_L(0); PG8_BAR; PG8_MMA(0, 0, At, B0); PG8_MMA(0, 1, At, B1); PG8_BAR; PG8_SCHED;
;             PG8_LDA(At, 0, 1); PG8_STAGE(PG8_SB(0, 0), b2, voffB); PG8_STAGE(PG8_SB(0, 1), b2 + hstepB, voffB); PG8_STAGE(PG8_SA(0, 0), a2, voffA);
;             PG8_WAIT_V(8); PG8_WAIT_L(0); PG8_BAR; PG8_MMA(1, 0, At, B0); PG8_MMA(1, 1, At, B1); PG8_BAR; PG8_SCHED;
	s_setprio 1
	s_waitcnt lgkmcnt(0)
	v_mfma_f32_16x16x32_bf16 v[124:127], v[128:131], v[170:173], v[124:127]
	v_mfma_f32_16x16x32_bf16 v[120:123], v[136:139], v[170:173], v[120:123]
	v_mfma_f32_16x16x32_bf16 v[108:111], v[128:131], v[178:181], v[108:111]
	v_mfma_f32_16x16x32_bf16 v[104:107], v[136:139], v[178:181], v[104:107]
	v_mfma_f32_16x16x32_bf16 v[92:95], v[128:131], v[200:203], v[92:95]
	v_mfma_f32_16x16x32_bf16 v[88:91], v[136:139], v[200:203], v[88:91]
	v_mfma_f32_16x16x32_bf16 v[76:79], v[128:131], v[208:211], v[76:79]
	v_mfma_f32_16x16x32_bf16 v[72:75], v[136:139], v[208:211], v[72:75]
	v_mfma_f32_16x16x32_bf16 v[124:127], v[132:135], v[174:177], v[124:127]
	v_mfma_f32_16x16x32_bf16 v[120:123], v[140:143], v[174:177], v[120:123]
	v_mfma_f32_16x16x32_bf16 v[108:111], v[132:135], v[182:185], v[108:111]
	v_mfma_f32_16x16x32_bf16 v[104:107], v[140:143], v[182:185], v[104:107]
	v_mfma_f32_16x16x32_bf16 v[92:95], v[132:135], v[204:207], v[92:95]
	v_mfma_f32_16x16x32_bf16 v[88:91], v[140:143], v[204:207], v[88:91]
	v_mfma_f32_16x16x32_bf16 v[76:79], v[132:135], v[212:215], v[76:79]
	v_mfma_f32_16x16x32_bf16 v[72:75], v[140:143], v[212:215], v[72:75]
	s_setprio 0
	s_setprio 1
	v_mfma_f32_16x16x32_bf16 v[116:119], v[144:147], v[170:173], v[116:119]
	v_mfma_f32_16x16x32_bf16 v[112:115], v[152:155], v[170:173], v[112:115]
	v_mfma_f32_16x16x32_bf16 v[100:103], v[144:147], v[178:181], v[100:103]
	v_mfma_f32_16x16x32_bf16 v[96:99], v[152:155], v[178:181], v[96:99]
	v_mfma_f32_16x16x32_bf16 v[84:87], v[144:147], v[200:203], v[84:87]
	v_mfma_f32_16x16x32_bf16 v[80:83], v[152:155], v[200:203], v[80:83]
	v_mfma_f32_16x16x32_bf16 v[68:71], v[144:147], v[208:211], v[68:71]
	v_mfma_f32_16x16x32_bf16 v[64:67], v[152:155], v[208:211], v[64:67]
	v_mfma_f32_16x16x32_bf16 v[116:119], v[148:151], v[174:177], v[116:119]
	v_mfma_f32_16x16x32_bf16 v[112:115], v[166:169], v[174:177], v[112:115]
	v_mfma_f32_16x16x32_bf16 v[100:103], v[148:151], v[182:185], v[100:103]
	v_mfma_f32_16x16x32_bf16 v[96:99], v[166:169], v[182:185], v[96:99]
	v_mfma_f32_16x16x32_bf16 v[84:87], v[148:151], v[204:207], v[84:87]
	v_mfma_f32_16x16x32_bf16 v[80:83], v[166:169], v[204:207], v[80:83]
	v_mfma_f32_16x16x32_bf16 v[68:71], v[148:151], v[212:215], v[68:71]
	v_mfma_f32_16x16x32_bf16 v[64:67], v[166:169], v[212:215], v[64:67]
	s_setprio 0
	s_barrier
	s_add_i32 s59, s59, s27
	v_lshl_add_u64 v[186:187], s[44:45], 0, v[192:193]
	s_mov_b32 m0, s59
	ds_read_b128 v[170:173], v191 offset:16384
	ds_read_b128 v[174:177], v191 offset:17408
	ds_read_b128 v[178:181], v191 offset:18432
	ds_read_b128 v[182:185], v191 offset:19456
	ds_read_b128 v[200:203], v191 offset:20480
	ds_read_b128 v[204:207], v191 offset:21504
	ds_read_b128 v[208:211], v191 offset:22528
	ds_read_b128 v[212:215], v191 offset:23552
	global_load_lds_dwordx4 v[186:187], off
	s_add_i32 m0, s59, 0x2000
	s_add_u32 s60, s44, 0x80000
	v_lshl_add_u64 v[216:217], s[44:45], 0, v[156:157]
	s_addc_u32 s61, s45, 0
	s_add_i32 s59, s66, s27
	global_load_lds_dwordx4 v[216:217], off
	v_lshl_add_u64 v[218:219], s[60:61], 0, v[192:193]
	s_mov_b32 m0, s59
	v_lshl_add_u64 v[228:229], s[46:47], 0, v[158:159]
	global_load_lds_dwordx4 v[218:219], off
	v_lshl_add_u64 v[218:219], s[60:61], 0, v[156:157]
	s_add_i32 m0, s59, 0x2000
	s_nop 0
	global_load_lds_dwordx4 v[218:219], off
	v_lshl_add_u64 v[218:219], s[46:47], 0, v[160:161]
	s_mov_b32 m0, s36
	s_nop 0
	global_load_lds_dwordx4 v[218:219], off
	s_mov_b32 m0, s42
	s_nop 0
	global_load_lds_dwordx4 v[228:229], off
	s_waitcnt vmcnt(8)
	s_waitcnt lgkmcnt(0)
	s_barrier
	s_setprio 1
	s_waitcnt lgkmcnt(0)
	v_mfma_f32_16x16x32_bf16 v[60:63], v[128:131], v[170:173], v[60:63]
	v_mfma_f32_16x16x32_bf16 v[56:59], v[136:139], v[170:173], v[56:59]
	v_mfma_f32_16x16x32_bf16 v[44:47], v[128:131], v[178:181], v[44:47]
	v_mfma_f32_16x16x32_bf16 v[40:43], v[136:139], v[178:181], v[40:43]
	v_mfma_f32_16x16x32_bf16 v[28:31], v[128:131], v[200:203], v[28:31]
	v_mfma_f32_16x16x32_bf16 v[24:27], v[136:139], v[200:203], v[24:27]
	v_mfma_f32_16x16x32_bf16 v[12:15], v[128:131], v[208:211], v[12:15]
	v_mfma_f32_16x16x32_bf16 v[8:11], v[136:139], v[208:211], v[8:11]
	v_mfma_f32_16x16x32_bf16 v[60:63], v[132:135], v[174:177], v[60:63]
	v_mfma_f32_16x16x32_bf16 v[56:59], v[140:143], v[174:177], v[56:59]
	v_mfma_f32_16x16x32_bf16 v[44:47], v[132:135], v[182:185], v[44:47]
	v_mfma_f32_16x16x32_bf16 v[40:43], v[140:143], v[182:185], v[40:43]
	v_mfma_f32_16x16x32_bf16 v[28:31], v[132:135], v[204:207], v[28:31]
	v_mfma_f32_16x16x32_bf16 v[24:27], v[140:143], v[204:207], v[24:27]
	v_mfma_f32_16x16x32_bf16 v[12:15], v[132:135], v[212:215], v[12:15]
	v_mfma_f32_16x16x32_bf16 v[8:11], v[140:143], v[212:215], v[8:11]
	s_setprio 0
	s_setprio 1
	v_mfma_f32_16x16x32_bf16 v[52:55], v[144:147], v[170:173], v[52:55]
	v_mfma_f32_16x16x32_bf16 v[48:51], v[152:155], v[170:173], v[48:51]
	v_mfma_f32_16x16x32_bf16 v[36:39], v[144:147], v[178:181], v[36:39]
	v_mfma_f32_16x16x32_bf16 v[32:35], v[152:155], v[178:181], v[32:35]
	v_mfma_f32_16x16x32_bf16 v[20:23], v[144:147], v[200:203], v[20:23]
	v_mfma_f32_16x16x32_bf16 v[16:19], v[152:155], v[200:203], v[16:19]
	v_mfma_f32_16x16x32_bf16 v[4:7], v[144:147], v[208:211], v[4:7]
	v_mfma_f32_16x16x32_bf16 v[0:3], v[152:155], v[208:211], v[0:3]
	v_mfma_f32_16x16x32_bf16 v[52:55], v[148:151], v[174:177], v[52:55]
	v_mfma_f32_16x16x32_bf16 v[48:51], v[166:169], v[174:177], v[48:51]
	v_mfma_f32_16x16x32_bf16 v[36:39], v[148:151], v[182:185], v[36:39]
	v_mfma_f32_16x16x32_bf16 v[32:35], v[166:169], v[182:185], v[32:35]
	v_mfma_f32_16x16x32_bf16 v[20:23], v[148:151], v[204:207], v[20:23]
	v_mfma_f32_16x16x32_bf16 v[16:19], v[166:169], v[204:207], v[16:19]
	v_mfma_f32_16x16x32_bf16 v[4:7], v[148:151], v[212:215], v[4:7]
	v_mfma_f32_16x16x32_bf16 v[0:3], v[166:169], v[212:215], v[0:3]
	s_setprio 0
	s_barrier
; #define PG8_STAGE(bufoff, gbase, voff) do { _Pragma("unroll") for (int _i = 0; _i < 2; ++_i) \
;         __builtin_amdgcn_global_load_lds((const unsigned*)((const char*)(gbase) + (voff)[_i]), (LAS unsigned*)(lds + (bufoff) + ldsw + _i * 8192), 16, 0, 0); } while (0)
; #define PG8_LDA(dst, b, h) do { _Pragma("unroll") for (int m = 0; m < 4; ++m) _Pragma("unroll") for (int k = 0; k < 2; ++k) dst[m][k] = *(const LAS bf16x8*)(lds + PG8_SA(b, h) + aoff + m * 2048 + k * 1024); } while (0)
; #define PG8_LDB(dst, b, h) do { _Pragma("unroll") for (int n = 0; n < 2; ++n) _Pragma("unroll") for (int k = 0; k < 2; ++k) dst[n][k] = *(const LAS bf16x8*)(lds + PG8_SB(b, h) + boff + n * 2048 + k * 1024); } while (0)
; #define PG8_MMA(ai, bj, At, Bt) do { __builtin_amdgcn_s_setprio(1); _Pragma("unroll") for (int m = 0; m < 4; ++m) _Pragma("unroll") for (int n = 0; n < 2; ++n) _Pragma("unroll") for (int k = 0; k < 2; ++k) \
;         acc[ai][bj][m][n] = __builtin_amdgcn_mfma_f32_16x16x32_bf16(Bt[n][k], At[m][k], acc[ai][bj][m][n], 0, 0, 0); __builtin_amdgcn_s_setprio(0); } while (0)
; #define PG8_WAIT_V(n) asm volatile("s_waitcnt vmcnt(" #n ")" ::: "memory")
; #define PG8_WAIT_L(n) asm volatile("s_waitcnt lgkmcnt(" #n ")" ::: "memory")
; #define PG8_BAR __builtin_amdgcn_s_barrier()
; #define PG8_SCHED __builtin_amdgcn_sched_barrier(0)
; template <class Epi, class Sched, bool ALIGN_EPI = false, bool SP2 = false>
; __device__ __forceinline__ void gemm_phase(LAS unsigned char* lds, const Gemm g, const Sched& S, const Epi& E, int wid) {
;     ...
;             PG8_LDB(B0, 1, 0); PG8_LDB(B1, 1, 1); PG8_SCHED; PG8_LDA(At, 1, 0); PG8_STAGE(PG8_SA(0, 1), a2 + hstepA, voffA);
;             PG8_WAIT_V(8); PG8_WAIT_L(0); PG8_BAR; PG8_MMA(0, 0, At, B0); PG8_MMA(0, 1, At, B1); PG8_BAR; PG8_SCHED;
	s_add_i32 s59, 0, 0x18000
	s_add_i32 s60, 0, 0x1c000
	v_add_u32_e32 v140, s59, v189
	v_add_u32_e32 v166, s60, v189
	ds_read_b128 v[128:131], v140
	ds_read_b128 v[132:135], v140 offset:1024
	ds_read_b128 v[136:139], v140 offset:2048
	ds_read_b128 v[140:143], v140 offset:3072
	ds_read_b128 v[144:147], v166
	ds_read_b128 v[148:151], v166 offset:1024
	ds_read_b128 v[152:155], v166 offset:2048
	ds_read_b128 v[166:169], v166 offset:3072
	s_add_u32 s46, s46, 0x80000
	s_addc_u32 s47, s47, 0
	s_mov_b32 m0, s43
	v_lshl_add_u64 v[230:231], s[46:47], 0, v[160:161]
	ds_read_b128 v[170:173], v191 offset:32768
	ds_read_b128 v[174:177], v191 offset:33792
	ds_read_b128 v[178:181], v191 offset:34816
	ds_read_b128 v[182:185], v191 offset:35840
	ds_read_b128 v[200:203], v191 offset:36864
	ds_read_b128 v[204:207], v191 offset:37888
	ds_read_b128 v[208:211], v191 offset:38912
	ds_read_b128 v[212:215], v191 offset:39936
	global_load_lds_dwordx4 v[230:231], off
	v_lshl_add_u64 v[230:231], s[46:47], 0, v[158:159]
	s_mov_b32 m0, s48
	s_nop 0
	global_load_lds_dwordx4 v[230:231], off
	s_waitcnt vmcnt(8)
	s_waitcnt lgkmcnt(0)
	s_barrier
	s_setprio 1
	s_waitcnt lgkmcnt(0)
	v_mfma_f32_16x16x32_bf16 v[124:127], v[128:131], v[170:173], v[124:127]
	v_mfma_f32_16x16x32_bf16 v[120:123], v[136:139], v[170:173], v[120:123]
	v_mfma_f32_16x16x32_bf16 v[108:111], v[128:131], v[178:181], v[108:111]
	v_mfma_f32_16x16x32_bf16 v[104:107], v[136:139], v[178:181], v[104:107]
	v_mfma_f32_16x16x32_bf16 v[92:95], v[128:131], v[200:203], v[92:95]
	v_mfma_f32_16x16x32_bf16 v[88:91], v[136:139], v[200:203], v[88:91]
	v_mfma_f32_16x16x32_bf16 v[76:79], v[128:131], v[208:211], v[76:79]
	v_mfma_f32_16x16x32_bf16 v[72:75], v[136:139], v[208:211], v[72:75]
	v_mfma_f32_16x16x32_bf16 v[124:127], v[132:135], v[174:177], v[124:127]
	v_mfma_f32_16x16x32_bf16 v[120:123], v[140:143], v[174:177], v[120:123]
	v_mfma_f32_16x16x32_bf16 v[108:111], v[132:135], v[182:185], v[108:111]
	v_mfma_f32_16x16x32_bf16 v[104:107], v[140:143], v[182:185], v[104:107]
	v_mfma_f32_16x16x32_bf16 v[92:95], v[132:135], v[204:207], v[92:95]
	v_mfma_f32_16x16x32_bf16 v[88:91], v[140:143], v[204:207], v[88:91]
	v_mfma_f32_16x16x32_bf16 v[76:79], v[132:135], v[212:215], v[76:79]
	v_mfma_f32_16x16x32_bf16 v[72:75], v[140:143], v[212:215], v[72:75]
	s_setprio 0
	s_setprio 1
	v_mfma_f32_16x16x32_bf16 v[116:119], v[144:147], v[170:173], v[116:119]
	v_mfma_f32_16x16x32_bf16 v[112:115], v[152:155], v[170:173], v[112:115]
	v_mfma_f32_16x16x32_bf16 v[100:103], v[144:147], v[178:181], v[100:103]
	v_mfma_f32_16x16x32_bf16 v[96:99], v[152:155], v[178:181], v[96:99]
	v_mfma_f32_16x16x32_bf16 v[84:87], v[144:147], v[200:203], v[84:87]
	v_mfma_f32_16x16x32_bf16 v[80:83], v[152:155], v[200:203], v[80:83]
	v_mfma_f32_16x16x32_bf16 v[68:71], v[144:147], v[208:211], v[68:71]
	v_mfma_f32_16x16x32_bf16 v[64:67], v[152:155], v[208:211], v[64:67]
	v_mfma_f32_16x16x32_bf16 v[116:119], v[148:151], v[174:177], v[116:119]
	v_mfma_f32_16x16x32_bf16 v[112:115], v[166:169], v[174:177], v[112:115]
	v_mfma_f32_16x16x32_bf16 v[100:103], v[148:151], v[182:185], v[100:103]
	v_mfma_f32_16x16x32_bf16 v[96:99], v[166:169], v[182:185], v[96:99]
	v_mfma_f32_16x16x32_bf16 v[84:87], v[148:151], v[204:207], v[84:87]
	v_mfma_f32_16x16x32_bf16 v[80:83], v[166:169], v[204:207], v[80:83]
	v_mfma_f32_16x16x32_bf16 v[68:71], v[148:151], v[212:215], v[68:71]
	v_mfma_f32_16x16x32_bf16 v[64:67], v[166:169], v[212:215], v[64:67]
	s_setprio 0
	s_barrier
; #define PG8_STAGE(bufoff, gbase, voff) do { _Pragma("unroll") for (int _i = 0; _i < 2; ++_i) \
;         __builtin_amdgcn_global_load_lds((const unsigned*)((const char*)(gbase) + (voff)[_i]), (LAS unsigned*)(lds + (bufoff) + ldsw + _i * 8192), 16, 0, 0); } while (0)
; #define PG8_LDA(dst, b, h) do { _Pragma("unroll") for (int m = 0; m < 4; ++m) _Pragma("unroll") for (int k = 0; k < 2; ++k) dst[m][k] = *(const LAS bf16x8*)(lds + PG8_SA(b, h) + aoff + m * 2048 + k * 1024); } while (0)
; #define PG8_MMA(ai, bj, At, Bt) do { __builtin_amdgcn_s_setprio(1); _Pragma("unroll") for (int m = 0; m < 4; ++m) _Pragma("unroll") for (int n = 0; n < 2; ++n) _Pragma("unroll") for (int k = 0; k < 2; ++k) \
;         acc[ai][bj][m][n] = __builtin_amdgcn_mfma_f32_16x16x32_bf16(Bt[n][k], At[m][k], acc[ai][bj][m][n], 0, 0, 0); __builtin_amdgcn_s_setprio(0); } while (0)
; #define PG8_WAIT_V(n) asm volatile("s_waitcnt vmcnt(" #n ")" ::: "memory")
; #define PG8_WAIT_L(n) asm volatile("s_waitcnt lgkmcnt(" #n ")" ::: "memory")
; #define PG8_BAR __builtin_amdgcn_s_barrier()
; #define PG8_SCHED __builtin_amdgcn_sched_barrier(0)
; template <class Epi, class Sched, bool ALIGN_EPI = false, bool SP2 = false>
; __device__ __forceinline__ void gemm_phase(LAS unsigned char* lds, const Gemm g, const Sched& S, const Epi& E, int wid) {
;     ...
;             PG8_LDA(At, 1, 1); PG8_STAGE(PG8_SB(1, 0), b3, voffB); PG8_STAGE(PG8_SB(1, 1), b3 + hstepB, voffB); PG8_STAGE(PG8_SA(1, 0), a3, voffA);
;             PG8_WAIT_V(8); PG8_WAIT_L(0); PG8_BAR; PG8_MMA(1, 0, At, B0); PG8_MMA(1, 1, At, B1); PG8_BAR; PG8_SCHED;
;     ...
;         if constexpr (ALIGN_EPI) { if (wr == 0) PG8_BAR; }
	s_add_i32 s46, s59, s27
	v_lshl_add_u64 v[186:187], v[186:187], 0, s[64:65]
	s_mov_b32 m0, s46
	ds_read_b128 v[170:173], v191 offset:49152
	ds_read_b128 v[174:177], v191 offset:50176
	ds_read_b128 v[178:181], v191 offset:51200
	ds_read_b128 v[182:185], v191 offset:52224
	ds_read_b128 v[200:203], v191 offset:53248
	ds_read_b128 v[204:207], v191 offset:54272
	ds_read_b128 v[208:211], v191 offset:55296
	ds_read_b128 v[212:215], v191 offset:56320
	global_load_lds_dwordx4 v[186:187], off
	s_add_i32 m0, s46, 0x2000
	s_add_u32 s44, s44, 0x80080
	v_lshl_add_u64 v[186:187], v[216:217], 0, s[64:65]
	s_addc_u32 s45, s45, 0
	s_add_i32 s46, s60, s27
	global_load_lds_dwordx4 v[186:187], off
	v_lshl_add_u64 v[186:187], s[44:45], 0, v[192:193]
	s_mov_b32 m0, s46
	s_nop 0
	global_load_lds_dwordx4 v[186:187], off
	v_lshl_add_u64 v[186:187], s[44:45], 0, v[156:157]
	s_add_i32 m0, s46, 0x2000
	s_nop 0
	global_load_lds_dwordx4 v[186:187], off
	v_lshl_add_u64 v[186:187], v[218:219], 0, s[64:65]
	s_mov_b32 m0, s49
	s_nop 0
	global_load_lds_dwordx4 v[186:187], off
	v_lshl_add_u64 v[186:187], v[228:229], 0, s[64:65]
	s_mov_b32 m0, s50
	s_nop 0
	global_load_lds_dwordx4 v[186:187], off
	s_waitcnt vmcnt(8)
	s_waitcnt lgkmcnt(0)
	s_barrier
	s_setprio 1
	s_waitcnt lgkmcnt(0)
	v_mfma_f32_16x16x32_bf16 v[60:63], v[128:131], v[170:173], v[60:63]
	v_mfma_f32_16x16x32_bf16 v[56:59], v[136:139], v[170:173], v[56:59]
	v_mfma_f32_16x16x32_bf16 v[44:47], v[128:131], v[178:181], v[44:47]
	v_mfma_f32_16x16x32_bf16 v[40:43], v[136:139], v[178:181], v[40:43]
	v_mfma_f32_16x16x32_bf16 v[28:31], v[128:131], v[200:203], v[28:31]
	v_mfma_f32_16x16x32_bf16 v[24:27], v[136:139], v[200:203], v[24:27]
	v_mfma_f32_16x16x32_bf16 v[12:15], v[128:131], v[208:211], v[12:15]
	v_mfma_f32_16x16x32_bf16 v[8:11], v[136:139], v[208:211], v[8:11]
	v_mfma_f32_16x16x32_bf16 v[60:63], v[132:135], v[174:177], v[60:63]
	v_mfma_f32_16x16x32_bf16 v[56:59], v[140:143], v[174:177], v[56:59]
	v_mfma_f32_16x16x32_bf16 v[44:47], v[132:135], v[182:185], v[44:47]
	v_mfma_f32_16x16x32_bf16 v[40:43], v[140:143], v[182:185], v[40:43]
	v_mfma_f32_16x16x32_bf16 v[28:31], v[132:135], v[204:207], v[28:31]
	v_mfma_f32_16x16x32_bf16 v[24:27], v[140:143], v[204:207], v[24:27]
	v_mfma_f32_16x16x32_bf16 v[12:15], v[132:135], v[212:215], v[12:15]
	v_mfma_f32_16x16x32_bf16 v[8:11], v[140:143], v[212:215], v[8:11]
	s_setprio 0
	s_setprio 1
	v_mfma_f32_16x16x32_bf16 v[52:55], v[144:147], v[170:173], v[52:55]
	v_mfma_f32_16x16x32_bf16 v[48:51], v[152:155], v[170:173], v[48:51]
	v_mfma_f32_16x16x32_bf16 v[36:39], v[144:147], v[178:181], v[36:39]
	v_mfma_f32_16x16x32_bf16 v[32:35], v[152:155], v[178:181], v[32:35]
	v_mfma_f32_16x16x32_bf16 v[20:23], v[144:147], v[200:203], v[20:23]
	v_mfma_f32_16x16x32_bf16 v[16:19], v[152:155], v[200:203], v[16:19]
	v_mfma_f32_16x16x32_bf16 v[4:7], v[144:147], v[208:211], v[4:7]
	v_mfma_f32_16x16x32_bf16 v[0:3], v[152:155], v[208:211], v[0:3]
	v_mfma_f32_16x16x32_bf16 v[52:55], v[148:151], v[174:177], v[52:55]
	v_mfma_f32_16x16x32_bf16 v[48:51], v[166:169], v[174:177], v[48:51]
	v_mfma_f32_16x16x32_bf16 v[36:39], v[148:151], v[182:185], v[36:39]
	v_mfma_f32_16x16x32_bf16 v[32:35], v[166:169], v[182:185], v[32:35]
	v_mfma_f32_16x16x32_bf16 v[20:23], v[148:151], v[204:207], v[20:23]
	v_mfma_f32_16x16x32_bf16 v[16:19], v[166:169], v[204:207], v[16:19]
	v_mfma_f32_16x16x32_bf16 v[4:7], v[148:151], v[212:215], v[4:7]
	v_mfma_f32_16x16x32_bf16 v[0:3], v[166:169], v[212:215], v[0:3]
	s_setprio 0
	s_barrier
	s_add_i32 s58, s58, 2
	s_add_u32 s40, s40, 0x100
	s_addc_u32 s41, s41, 0
	s_add_u32 s56, s56, 0x100
	s_addc_u32 s57, s57, 0
	s_cmp_gt_u32 s58, 29
	s_cbranch_scc0 .LBB0_881
	s_and_b64 vcc, exec, s[18:19]
	s_cbranch_vccz .LBB0_884
	s_barrier

; template <class Epi, class Sched, bool ALIGN_EPI = false, bool SP2 = false>
; __device__ __forceinline__ void gemm_phase(LAS unsigned char* lds, const Gemm g, const Sched& S, const Epi& E, int wid) {
;     ...
;         if (!has_next) break;
; #pragma unroll
;         for (int a = 0; a < 2; ++a)
; #pragma unroll
;             for (int b = 0; b < 2; ++b)
; #pragma unroll
;                 for (int m = 0; m < 4; ++m)
; #pragma unroll
;                     for (int n = 0; n < 2; ++n) acc[a][b][m][n] = (f32x4){0.f, 0.f, 0.f, 0.f};
;         cur = nxt; cA = nA; cB = nB; ++ui;
.LBB0_967:
	s_ashr_i32 s41, s40, 31
	s_lshl_b64 s[42:43], s[40:41], 20
	s_add_u32 s50, s97, s42
	s_addc_u32 s51, s27, s43
	s_and_b64 s[42:43], s[10:11], exec
	s_cselect_b32 s41, s51, s55
	s_cselect_b32 s42, s50, s54
	s_ashr_i32 s93, s92, 31
	s_lshl_b64 s[48:49], s[92:93], 20
	s_add_u32 s52, s6, s48
	s_addc_u32 s53, s7, s49
	s_and_b64 s[48:49], s[10:11], exec
	s_cselect_b32 s43, s53, s57
	s_cselect_b32 s59, s52, s56
	s_add_u32 s60, s56, 0x100
	v_mov_b32_e32 v8, 0
	s_addc_u32 s61, s57, 0
	s_mov_b32 s93, -2
	v_mov_b32_e32 v9, v8
	v_mov_b32_e32 v10, v8
	v_mov_b32_e32 v11, v8
	v_mov_b32_e32 v64, v8
	v_mov_b32_e32 v65, v8
	v_mov_b32_e32 v66, v8
	v_mov_b32_e32 v67, v8
	v_mov_b32_e32 v12, v8
	v_mov_b32_e32 v13, v8
	v_mov_b32_e32 v14, v8
	v_mov_b32_e32 v15, v8
	v_mov_b32_e32 v68, v8
	v_mov_b32_e32 v69, v8
	v_mov_b32_e32 v70, v8
	v_mov_b32_e32 v71, v8
	v_mov_b32_e32 v0, v8
	v_mov_b32_e32 v1, v8
	v_mov_b32_e32 v2, v8
	v_mov_b32_e32 v3, v8
	v_mov_b32_e32 v76, v8
	v_mov_b32_e32 v77, v8
	v_mov_b32_e32 v78, v8
	v_mov_b32_e32 v79, v8
	v_mov_b32_e32 v20, v8
	v_mov_b32_e32 v21, v8
	v_mov_b32_e32 v22, v8
	v_mov_b32_e32 v23, v8
	v_mov_b32_e32 v84, v8
	v_mov_b32_e32 v85, v8
	v_mov_b32_e32 v86, v8
	v_mov_b32_e32 v87, v8
	v_mov_b32_e32 v16, v8
	v_mov_b32_e32 v17, v8
	v_mov_b32_e32 v18, v8
	v_mov_b32_e32 v19, v8
	v_mov_b32_e32 v72, v8
	v_mov_b32_e32 v73, v8
	v_mov_b32_e32 v74, v8
	v_mov_b32_e32 v75, v8
	v_mov_b32_e32 v24, v8
	v_mov_b32_e32 v25, v8
	v_mov_b32_e32 v26, v8
	v_mov_b32_e32 v27, v8
	v_mov_b32_e32 v80, v8
	v_mov_b32_e32 v81, v8
	v_mov_b32_e32 v82, v8
	v_mov_b32_e32 v83, v8
	v_mov_b32_e32 v4, v8
	v_mov_b32_e32 v5, v8
	v_mov_b32_e32 v6, v8
	v_mov_b32_e32 v7, v8
	v_mov_b32_e32 v88, v8
	v_mov_b32_e32 v89, v8
	v_mov_b32_e32 v90, v8
	v_mov_b32_e32 v91, v8
	v_mov_b32_e32 v28, v8
	v_mov_b32_e32 v29, v8
	v_mov_b32_e32 v30, v8
	v_mov_b32_e32 v31, v8
	v_mov_b32_e32 v92, v8
	v_mov_b32_e32 v93, v8
	v_mov_b32_e32 v94, v8
	v_mov_b32_e32 v95, v8
	v_mov_b32_e32 v40, v8
	v_mov_b32_e32 v41, v8
	v_mov_b32_e32 v42, v8
	v_mov_b32_e32 v43, v8
	v_mov_b32_e32 v96, v8
	v_mov_b32_e32 v97, v8
	v_mov_b32_e32 v98, v8
	v_mov_b32_e32 v99, v8
	v_mov_b32_e32 v44, v8
	v_mov_b32_e32 v45, v8
	v_mov_b32_e32 v46, v8
	v_mov_b32_e32 v47, v8
	v_mov_b32_e32 v136, v8
	v_mov_b32_e32 v137, v8
	v_mov_b32_e32 v138, v8
	v_mov_b32_e32 v139, v8
	v_mov_b32_e32 v32, v8
	v_mov_b32_e32 v33, v8
	v_mov_b32_e32 v34, v8
	v_mov_b32_e32 v35, v8
	v_mov_b32_e32 v148, v8
	v_mov_b32_e32 v149, v8
	v_mov_b32_e32 v150, v8
	v_mov_b32_e32 v151, v8
	v_mov_b32_e32 v52, v8
	v_mov_b32_e32 v53, v8
	v_mov_b32_e32 v54, v8
	v_mov_b32_e32 v55, v8
	v_mov_b32_e32 v156, v8
	v_mov_b32_e32 v157, v8
	v_mov_b32_e32 v158, v8
	v_mov_b32_e32 v159, v8
	v_mov_b32_e32 v48, v8
	v_mov_b32_e32 v49, v8
	v_mov_b32_e32 v50, v8
	v_mov_b32_e32 v51, v8
	v_mov_b32_e32 v100, v8
	v_mov_b32_e32 v101, v8
	v_mov_b32_e32 v102, v8
	v_mov_b32_e32 v103, v8
	v_mov_b32_e32 v56, v8
	v_mov_b32_e32 v57, v8
	v_mov_b32_e32 v58, v8
	v_mov_b32_e32 v59, v8
	v_mov_b32_e32 v140, v8
	v_mov_b32_e32 v141, v8
	v_mov_b32_e32 v142, v8
	v_mov_b32_e32 v143, v8
	v_mov_b32_e32 v36, v8
	v_mov_b32_e32 v37, v8
	v_mov_b32_e32 v38, v8
	v_mov_b32_e32 v39, v8
	v_mov_b32_e32 v152, v8
	v_mov_b32_e32 v153, v8
	v_mov_b32_e32 v154, v8
	v_mov_b32_e32 v155, v8
	v_mov_b32_e32 v60, v8
	v_mov_b32_e32 v61, v8
	v_mov_b32_e32 v62, v8
	v_mov_b32_e32 v63, v8
	v_mov_b32_e32 v160, v8
	v_mov_b32_e32 v161, v8
	v_mov_b32_e32 v162, v8
	v_mov_b32_e32 v163, v8

; #define PG8_STAGE(bufoff, gbase, voff) do { _Pragma("unroll") for (int _i = 0; _i < 2; ++_i) \
;         __builtin_amdgcn_global_load_lds((const unsigned*)((const char*)(gbase) + (voff)[_i]), (LAS unsigned*)(lds + (bufoff) + ldsw + _i * 8192), 16, 0, 0); } while (0)
; #define PG8_LDA(dst, b, h) do { _Pragma("unroll") for (int m = 0; m < 4; ++m) _Pragma("unroll") for (int k = 0; k < 2; ++k) dst[m][k] = *(const LAS bf16x8*)(lds + PG8_SA(b, h) + aoff + m * 2048 + k * 1024); } while (0)
; #define PG8_LDB(dst, b, h) do { _Pragma("unroll") for (int n = 0; n < 2; ++n) _Pragma("unroll") for (int k = 0; k < 2; ++k) dst[n][k] = *(const LAS bf16x8*)(lds + PG8_SB(b, h) + boff + n * 2048 + k * 1024); } while (0)
; #define PG8_MMA(ai, bj, At, Bt) do { __builtin_amdgcn_s_setprio(1); _Pragma("unroll") for (int m = 0; m < 4; ++m) _Pragma("unroll") for (int n = 0; n < 2; ++n) _Pragma("unroll") for (int k = 0; k < 2; ++k) \
;         acc[ai][bj][m][n] = __builtin_amdgcn_mfma_f32_16x16x32_bf16(Bt[n][k], At[m][k], acc[ai][bj][m][n], 0, 0, 0); __builtin_amdgcn_s_setprio(0); } while (0)
; #define PG8_WAIT_V(n) asm volatile("s_waitcnt vmcnt(" #n ")" ::: "memory")
; #define PG8_WAIT_L(n) asm volatile("s_waitcnt lgkmcnt(" #n ")" ::: "memory")
; template <class Epi, class Sched, bool ALIGN_EPI = false, bool SP2 = false>
; __device__ __forceinline__ void gemm_phase(LAS unsigned char* lds, const Gemm g, const Sched& S, const Epi& E, int wid) {
;     ...
;             const bool last = (t == nt - 2);
;             const char* a1 = cA + (size_t)(t + 1) * kstep;
;             const char* a2 = last ? nA : cA + (size_t)(t + 2) * kstep; const char* b2 = last ? nB : cB + (size_t)(t + 2) * kstep;
;             const char* a3 = a2 + kstep; const char* b3 = b2 + kstep;
;             if constexpr (SP2) {
;             PG8_LDB(B0, 0, 0); PG8_LDB(B1, 0, 1); PG8_SCHED; PG8_LDA(At, 0, 0); PG8_STAGE(PG8_SA(1, 1), a1 + hstepA, voffA);
;             PG8_WAIT_V(8); PG8_WAIT_L(0); PG8_BAR; PG8_MMA(0, 0, At, B0); PG8_MMA(0, 1, At, B1); PG8_BAR; PG8_SCHED;
;     ...
; #pragma unroll
;         for (int a = 0; a < 2; ++a)
; #pragma unroll
;             for (int b = 0; b < 2; ++b)
; #pragma unroll
;                 for (int m = 0; m < 4; ++m)
; #pragma unroll
;                     for (int n = 0; n < 2; ++n) acc[a][b][m][n] = (f32x4){0.f, 0.f, 0.f, 0.f};
;         cur = nxt; cA = nA; cB = nB; ++ui;
.LBB0_1150:
	s_add_u32 s56, s40, 0x100
	v_mov_b32_e32 v0, 0
	s_addc_u32 s57, s41, 0
	s_mov_b32 s58, -2
	v_mov_b32_e32 v1, v0
	v_mov_b32_e32 v2, v0
	v_mov_b32_e32 v3, v0
	v_mov_b32_e32 v4, v0
	v_mov_b32_e32 v5, v0
	v_mov_b32_e32 v6, v0
	v_mov_b32_e32 v7, v0
	v_mov_b32_e32 v16, v0
	v_mov_b32_e32 v17, v0
	v_mov_b32_e32 v18, v0
	v_mov_b32_e32 v19, v0
	v_mov_b32_e32 v20, v0
	v_mov_b32_e32 v21, v0
	v_mov_b32_e32 v22, v0
	v_mov_b32_e32 v23, v0
	v_mov_b32_e32 v32, v0
	v_mov_b32_e32 v33, v0
	v_mov_b32_e32 v34, v0
	v_mov_b32_e32 v35, v0
	v_mov_b32_e32 v36, v0
	v_mov_b32_e32 v37, v0
	v_mov_b32_e32 v38, v0
	v_mov_b32_e32 v39, v0
	v_mov_b32_e32 v48, v0
	v_mov_b32_e32 v49, v0
	v_mov_b32_e32 v50, v0
	v_mov_b32_e32 v51, v0
	v_mov_b32_e32 v52, v0
	v_mov_b32_e32 v53, v0
	v_mov_b32_e32 v54, v0
	v_mov_b32_e32 v55, v0
	v_mov_b32_e32 v8, v0
	v_mov_b32_e32 v9, v0
	v_mov_b32_e32 v10, v0
	v_mov_b32_e32 v11, v0
	v_mov_b32_e32 v12, v0
	v_mov_b32_e32 v13, v0
	v_mov_b32_e32 v14, v0
	v_mov_b32_e32 v15, v0
	v_mov_b32_e32 v24, v0
	v_mov_b32_e32 v25, v0
	v_mov_b32_e32 v26, v0
	v_mov_b32_e32 v27, v0
	v_mov_b32_e32 v28, v0
	v_mov_b32_e32 v29, v0
	v_mov_b32_e32 v30, v0
	v_mov_b32_e32 v31, v0
	v_mov_b32_e32 v40, v0
	v_mov_b32_e32 v41, v0
	v_mov_b32_e32 v42, v0
	v_mov_b32_e32 v43, v0
	v_mov_b32_e32 v44, v0
	v_mov_b32_e32 v45, v0
	v_mov_b32_e32 v46, v0
	v_mov_b32_e32 v47, v0
	v_mov_b32_e32 v56, v0
	v_mov_b32_e32 v57, v0
	v_mov_b32_e32 v58, v0
	v_mov_b32_e32 v59, v0
	v_mov_b32_e32 v60, v0
	v_mov_b32_e32 v61, v0
	v_mov_b32_e32 v62, v0
	v_mov_b32_e32 v63, v0
	v_mov_b32_e32 v64, v0
	v_mov_b32_e32 v65, v0
	v_mov_b32_e32 v66, v0
	v_mov_b32_e32 v67, v0
	v_mov_b32_e32 v68, v0
	v_mov_b32_e32 v69, v0
	v_mov_b32_e32 v70, v0
	v_mov_b32_e32 v71, v0
	v_mov_b32_e32 v80, v0
	v_mov_b32_e32 v81, v0
	v_mov_b32_e32 v82, v0
	v_mov_b32_e32 v83, v0
	v_mov_b32_e32 v84, v0
	v_mov_b32_e32 v85, v0
	v_mov_b32_e32 v86, v0
	v_mov_b32_e32 v87, v0
	v_mov_b32_e32 v96, v0
	v_mov_b32_e32 v97, v0
	v_mov_b32_e32 v98, v0
	v_mov_b32_e32 v99, v0
	v_mov_b32_e32 v100, v0
	v_mov_b32_e32 v101, v0
	v_mov_b32_e32 v102, v0
	v_mov_b32_e32 v103, v0
	v_mov_b32_e32 v112, v0
	v_mov_b32_e32 v113, v0
	v_mov_b32_e32 v114, v0
	v_mov_b32_e32 v115, v0
	v_mov_b32_e32 v116, v0
	v_mov_b32_e32 v117, v0
	v_mov_b32_e32 v118, v0
	v_mov_b32_e32 v119, v0
	v_mov_b32_e32 v72, v0
	v_mov_b32_e32 v73, v0
	v_mov_b32_e32 v74, v0
	v_mov_b32_e32 v75, v0
	v_mov_b32_e32 v76, v0
	v_mov_b32_e32 v77, v0
	v_mov_b32_e32 v78, v0
	v_mov_b32_e32 v79, v0
	v_mov_b32_e32 v88, v0
	v_mov_b32_e32 v89, v0
	v_mov_b32_e32 v90, v0
	v_mov_b32_e32 v91, v0
	v_mov_b32_e32 v92, v0
	v_mov_b32_e32 v93, v0
	v_mov_b32_e32 v94, v0
	v_mov_b32_e32 v95, v0
	v_mov_b32_e32 v104, v0
	v_mov_b32_e32 v105, v0
	v_mov_b32_e32 v106, v0
	v_mov_b32_e32 v107, v0
	v_mov_b32_e32 v108, v0
	v_mov_b32_e32 v109, v0
	v_mov_b32_e32 v110, v0
	v_mov_b32_e32 v111, v0
	v_mov_b32_e32 v120, v0
	v_mov_b32_e32 v121, v0
	v_mov_b32_e32 v122, v0
	v_mov_b32_e32 v123, v0
	v_mov_b32_e32 v124, v0
	v_mov_b32_e32 v125, v0
	v_mov_b32_e32 v126, v0
	v_mov_b32_e32 v127, v0
.LBB0_1151:
	s_add_u32 s40, s38, 0x100
	s_addc_u32 s41, s39, 0
	s_add_i32 s59, 0, 0x10000
	s_cmpk_eq_i32 s58, 0x54
	s_cselect_b32 s47, s13, s41
	s_cselect_b32 s46, s12, s40
	s_cselect_b32 s45, s35, s57
	s_cselect_b32 s44, s34, s56
	s_add_i32 s60, 0, 0x14000
	v_add_u32_e32 v140, s59, v183
	v_add_u32_e32 v166, s60, v183
	ds_read_b128 v[128:131], v140
	ds_read_b128 v[132:135], v140 offset:1024
	ds_read_b128 v[136:139], v140 offset:2048
	ds_read_b128 v[140:143], v140 offset:3072
	ds_read_b128 v[144:147], v166
	ds_read_b128 v[148:151], v166 offset:1024
	ds_read_b128 v[152:155], v166 offset:2048
	ds_read_b128 v[166:169], v166 offset:3072
	v_lshl_add_u64 v[190:191], s[38:39], 0, v[162:163]
	s_add_i32 m0, s36, 0xc000
	ds_read_b128 v[170:173], v185
	ds_read_b128 v[174:177], v185 offset:1024
	ds_read_b128 v[178:181], v185 offset:2048
	ds_read_b128 v[186:189], v185 offset:3072
	ds_read_b128 v[200:203], v185 offset:4096
	ds_read_b128 v[204:207], v185 offset:5120
	ds_read_b128 v[208:211], v185 offset:6144
	ds_read_b128 v[212:215], v185 offset:7168
	global_load_lds_dwordx4 v[190:191], off
	v_lshl_add_u64 v[190:191], s[38:39], 0, v[164:165]
	s_add_i32 m0, s36, 0xe000
	s_nop 0
	global_load_lds_dwordx4 v[190:191], off
	s_waitcnt vmcnt(8)
	s_waitcnt lgkmcnt(0)
	s_barrier
	s_setprio 1
	s_waitcnt lgkmcnt(0)
	v_mfma_f32_16x16x32_bf16 v[124:127], v[128:131], v[170:173], v[124:127]
	v_mfma_f32_16x16x32_bf16 v[120:123], v[136:139], v[170:173], v[120:123]
	v_mfma_f32_16x16x32_bf16 v[108:111], v[128:131], v[178:181], v[108:111]
	v_mfma_f32_16x16x32_bf16 v[104:107], v[136:139], v[178:181], v[104:107]
	v_mfma_f32_16x16x32_bf16 v[92:95], v[128:131], v[200:203], v[92:95]
	v_mfma_f32_16x16x32_bf16 v[88:91], v[136:139], v[200:203], v[88:91]
	v_mfma_f32_16x16x32_bf16 v[76:79], v[128:131], v[208:211], v[76:79]
	v_mfma_f32_16x16x32_bf16 v[72:75], v[136:139], v[208:211], v[72:75]
	v_mfma_f32_16x16x32_bf16 v[124:127], v[132:135], v[174:177], v[124:127]
	v_mfma_f32_16x16x32_bf16 v[120:123], v[140:143], v[174:177], v[120:123]
	v_mfma_f32_16x16x32_bf16 v[108:111], v[132:135], v[186:189], v[108:111]
	v_mfma_f32_16x16x32_bf16 v[104:107], v[140:143], v[186:189], v[104:107]
	v_mfma_f32_16x16x32_bf16 v[92:95], v[132:135], v[204:207], v[92:95]
	v_mfma_f32_16x16x32_bf16 v[88:91], v[140:143], v[204:207], v[88:91]
	v_mfma_f32_16x16x32_bf16 v[76:79], v[132:135], v[212:215], v[76:79]
	v_mfma_f32_16x16x32_bf16 v[72:75], v[140:143], v[212:215], v[72:75]
	s_setprio 0
	s_setprio 1
	v_mfma_f32_16x16x32_bf16 v[116:119], v[144:147], v[170:173], v[116:119]
	v_mfma_f32_16x16x32_bf16 v[112:115], v[152:155], v[170:173], v[112:115]
	v_mfma_f32_16x16x32_bf16 v[100:103], v[144:147], v[178:181], v[100:103]
	v_mfma_f32_16x16x32_bf16 v[96:99], v[152:155], v[178:181], v[96:99]
	v_mfma_f32_16x16x32_bf16 v[84:87], v[144:147], v[200:203], v[84:87]
	v_mfma_f32_16x16x32_bf16 v[80:83], v[152:155], v[200:203], v[80:83]
	v_mfma_f32_16x16x32_bf16 v[68:71], v[144:147], v[208:211], v[68:71]
	v_mfma_f32_16x16x32_bf16 v[64:67], v[152:155], v[208:211], v[64:67]
	v_mfma_f32_16x16x32_bf16 v[116:119], v[148:151], v[174:177], v[116:119]
	v_mfma_f32_16x16x32_bf16 v[112:115], v[166:169], v[174:177], v[112:115]
	v_mfma_f32_16x16x32_bf16 v[100:103], v[148:151], v[186:189], v[100:103]
	v_mfma_f32_16x16x32_bf16 v[96:99], v[166:169], v[186:189], v[96:99]
	v_mfma_f32_16x16x32_bf16 v[84:87], v[148:151], v[204:207], v[84:87]
	v_mfma_f32_16x16x32_bf16 v[80:83], v[166:169], v[204:207], v[80:83]
	v_mfma_f32_16x16x32_bf16 v[68:71], v[148:151], v[212:215], v[68:71]
	v_mfma_f32_16x16x32_bf16 v[64:67], v[166:169], v[212:215], v[64:67]
	s_setprio 0
	s_barrier
; #define PG8_STAGE(bufoff, gbase, voff) do { _Pragma("unroll") for (int _i = 0; _i < 2; ++_i) \
;         __builtin_amdgcn_global_load_lds((const unsigned*)((const char*)(gbase) + (voff)[_i]), (LAS unsigned*)(lds + (bufoff) + ldsw + _i * 8192), 16, 0, 0); } while (0)
; #define PG8_LDA(dst, b, h) do { _Pragma("unroll") for (int m = 0; m < 4; ++m) _Pragma("unroll") for (int k = 0; k < 2; ++k) dst[m][k] = *(const LAS bf16x8*)(lds + PG8_SA(b, h) + aoff + m * 2048 + k * 1024); } while (0)
; #define PG8_LDB(dst, b, h) do { _Pragma("unroll") for (int n = 0; n < 2; ++n) _Pragma("unroll") for (int k = 0; k < 2; ++k) dst[n][k] = *(const LAS bf16x8*)(lds + PG8_SB(b, h) + boff + n * 2048 + k * 1024); } while (0)
; #define PG8_MMA(ai, bj, At, Bt) do { __builtin_amdgcn_s_setprio(1); _Pragma("unroll") for (int m = 0; m < 4; ++m) _Pragma("unroll") for (int n = 0; n < 2; ++n) _Pragma("unroll") for (int k = 0; k < 2; ++k) \
;         acc[ai][bj][m][n] = __builtin_amdgcn_mfma_f32_16x16x32_bf16(Bt[n][k], At[m][k], acc[ai][bj][m][n], 0, 0, 0); __builtin_amdgcn_s_setprio(0); } while (0)
; #define PG8_WAIT_V(n) asm volatile("s_waitcnt vmcnt(" #n ")" ::: "memory")
; #define PG8_WAIT_L(n) asm volatile("s_waitcnt lgkmcnt(" #n ")" ::: "memory")
; #define PG8_BAR __builtin_amdgcn_s_barrier()
; #define PG8_SCHED __builtin_amdgcn_sched_barrier(0)
; template <class Epi, class Sched, bool ALIGN_EPI = false, bool SP2 = false>
; __device__ __forceinline__ void gemm_phase(LAS unsigned char* lds, const Gemm g, const Sched& S, const Epi& E, int wid) {
;     ...
;             PG8_LDA(At, 0, 1); PG8_STAGE(PG8_SB(0, 0), b2, voffB); PG8_STAGE(PG8_SB(0, 1), b2 + hstepB, voffB); PG8_STAGE(PG8_SA(0, 0), a2, voffA);
;             PG8_WAIT_V(8); PG8_WAIT_L(0); PG8_BAR; PG8_MMA(1, 0, At, B0); PG8_MMA(1, 1, At, B1); PG8_BAR; PG8_SCHED;
;             PG8_LDB(B0, 1, 0); PG8_LDB(B1, 1, 1); PG8_SCHED; PG8_LDA(At, 1, 0); PG8_STAGE(PG8_SA(0, 1), a2 + hstepA, voffA);
;             PG8_WAIT_V(8); PG8_WAIT_L(0); PG8_BAR; PG8_MMA(0, 0, At, B0); PG8_MMA(0, 1, At, B1); PG8_BAR; PG8_SCHED;
	s_add_i32 s38, s59, s27
	v_lshl_add_u64 v[190:191], s[44:45], 0, v[192:193]
	s_mov_b32 m0, s38
	ds_read_b128 v[170:173], v185 offset:16384
	ds_read_b128 v[174:177], v185 offset:17408
	ds_read_b128 v[178:181], v185 offset:18432
	ds_read_b128 v[186:189], v185 offset:19456
	ds_read_b128 v[200:203], v185 offset:20480
	ds_read_b128 v[204:207], v185 offset:21504
	ds_read_b128 v[208:211], v185 offset:22528
	ds_read_b128 v[212:215], v185 offset:23552
	global_load_lds_dwordx4 v[190:191], off
	s_add_i32 m0, s38, 0x2000
	s_add_u32 s38, s44, 0x160000
	v_lshl_add_u64 v[216:217], s[44:45], 0, v[156:157]
	s_addc_u32 s39, s45, 0
	s_add_i32 s59, s60, s27
	global_load_lds_dwordx4 v[216:217], off
	v_lshl_add_u64 v[218:219], s[38:39], 0, v[192:193]
	s_mov_b32 m0, s59
	v_lshl_add_u64 v[228:229], s[46:47], 0, v[158:159]
	global_load_lds_dwordx4 v[218:219], off
	v_lshl_add_u64 v[218:219], s[38:39], 0, v[156:157]
	s_add_i32 m0, s59, 0x2000
	s_nop 0
	global_load_lds_dwordx4 v[218:219], off
	v_lshl_add_u64 v[218:219], s[46:47], 0, v[160:161]
	s_mov_b32 m0, s36
	s_nop 0
	global_load_lds_dwordx4 v[218:219], off
	s_mov_b32 m0, s42
	s_nop 0
	global_load_lds_dwordx4 v[228:229], off
	s_waitcnt vmcnt(8)
	s_waitcnt lgkmcnt(0)
	s_barrier
	s_setprio 1
	s_waitcnt lgkmcnt(0)
	v_mfma_f32_16x16x32_bf16 v[60:63], v[128:131], v[170:173], v[60:63]
	v_mfma_f32_16x16x32_bf16 v[56:59], v[136:139], v[170:173], v[56:59]
	v_mfma_f32_16x16x32_bf16 v[44:47], v[128:131], v[178:181], v[44:47]
	v_mfma_f32_16x16x32_bf16 v[40:43], v[136:139], v[178:181], v[40:43]
	v_mfma_f32_16x16x32_bf16 v[28:31], v[128:131], v[200:203], v[28:31]
	v_mfma_f32_16x16x32_bf16 v[24:27], v[136:139], v[200:203], v[24:27]
	v_mfma_f32_16x16x32_bf16 v[12:15], v[128:131], v[208:211], v[12:15]
	v_mfma_f32_16x16x32_bf16 v[8:11], v[136:139], v[208:211], v[8:11]
	v_mfma_f32_16x16x32_bf16 v[60:63], v[132:135], v[174:177], v[60:63]
	v_mfma_f32_16x16x32_bf16 v[56:59], v[140:143], v[174:177], v[56:59]
	v_mfma_f32_16x16x32_bf16 v[44:47], v[132:135], v[186:189], v[44:47]
	v_mfma_f32_16x16x32_bf16 v[40:43], v[140:143], v[186:189], v[40:43]
	v_mfma_f32_16x16x32_bf16 v[28:31], v[132:135], v[204:207], v[28:31]
	v_mfma_f32_16x16x32_bf16 v[24:27], v[140:143], v[204:207], v[24:27]
	v_mfma_f32_16x16x32_bf16 v[12:15], v[132:135], v[212:215], v[12:15]
	v_mfma_f32_16x16x32_bf16 v[8:11], v[140:143], v[212:215], v[8:11]
	s_setprio 0
	s_setprio 1
	v_mfma_f32_16x16x32_bf16 v[52:55], v[144:147], v[170:173], v[52:55]
	v_mfma_f32_16x16x32_bf16 v[48:51], v[152:155], v[170:173], v[48:51]
	v_mfma_f32_16x16x32_bf16 v[36:39], v[144:147], v[178:181], v[36:39]
	v_mfma_f32_16x16x32_bf16 v[32:35], v[152:155], v[178:181], v[32:35]
	v_mfma_f32_16x16x32_bf16 v[20:23], v[144:147], v[200:203], v[20:23]
	v_mfma_f32_16x16x32_bf16 v[16:19], v[152:155], v[200:203], v[16:19]
	v_mfma_f32_16x16x32_bf16 v[4:7], v[144:147], v[208:211], v[4:7]
	v_mfma_f32_16x16x32_bf16 v[0:3], v[152:155], v[208:211], v[0:3]
	v_mfma_f32_16x16x32_bf16 v[52:55], v[148:151], v[174:177], v[52:55]
	v_mfma_f32_16x16x32_bf16 v[48:51], v[166:169], v[174:177], v[48:51]
	v_mfma_f32_16x16x32_bf16 v[36:39], v[148:151], v[186:189], v[36:39]
	v_mfma_f32_16x16x32_bf16 v[32:35], v[166:169], v[186:189], v[32:35]
	v_mfma_f32_16x16x32_bf16 v[20:23], v[148:151], v[204:207], v[20:23]
	v_mfma_f32_16x16x32_bf16 v[16:19], v[166:169], v[204:207], v[16:19]
	v_mfma_f32_16x16x32_bf16 v[4:7], v[148:151], v[212:215], v[4:7]
	v_mfma_f32_16x16x32_bf16 v[0:3], v[166:169], v[212:215], v[0:3]
	s_setprio 0
	s_barrier
	s_add_i32 s59, 0, 0x18000
	s_add_i32 s60, 0, 0x1c000
	v_add_u32_e32 v140, s59, v183
	v_add_u32_e32 v166, s60, v183
	ds_read_b128 v[128:131], v140
	ds_read_b128 v[132:135], v140 offset:1024
	ds_read_b128 v[136:139], v140 offset:2048
	ds_read_b128 v[140:143], v140 offset:3072
	ds_read_b128 v[144:147], v166
	ds_read_b128 v[148:151], v166 offset:1024
	ds_read_b128 v[152:155], v166 offset:2048
	ds_read_b128 v[166:169], v166 offset:3072
	s_add_u32 s38, s46, 0x160000
	s_addc_u32 s39, s47, 0
	s_mov_b32 m0, s43
	v_lshl_add_u64 v[230:231], s[38:39], 0, v[160:161]
	ds_read_b128 v[170:173], v185 offset:32768
	ds_read_b128 v[174:177], v185 offset:33792
	ds_read_b128 v[178:181], v185 offset:34816
	ds_read_b128 v[186:189], v185 offset:35840
	ds_read_b128 v[200:203], v185 offset:36864
	ds_read_b128 v[204:207], v185 offset:37888
	ds_read_b128 v[208:211], v185 offset:38912
	ds_read_b128 v[212:215], v185 offset:39936
	global_load_lds_dwordx4 v[230:231], off
	v_lshl_add_u64 v[230:231], s[38:39], 0, v[158:159]
	s_mov_b32 m0, s48
	s_nop 0
	global_load_lds_dwordx4 v[230:231], off
	s_waitcnt vmcnt(8)
	s_waitcnt lgkmcnt(0)
	s_barrier
; #define PG8_STAGE(bufoff, gbase, voff) do { _Pragma("unroll") for (int _i = 0; _i < 2; ++_i) \
;         __builtin_amdgcn_global_load_lds((const unsigned*)((const char*)(gbase) + (voff)[_i]), (LAS unsigned*)(lds + (bufoff) + ldsw + _i * 8192), 16, 0, 0); } while (0)
; #define PG8_LDA(dst, b, h) do { _Pragma("unroll") for (int m = 0; m < 4; ++m) _Pragma("unroll") for (int k = 0; k < 2; ++k) dst[m][k] = *(const LAS bf16x8*)(lds + PG8_SA(b, h) + aoff + m * 2048 + k * 1024); } while (0)
; #define PG8_MMA(ai, bj, At, Bt) do { __builtin_amdgcn_s_setprio(1); _Pragma("unroll") for (int m = 0; m < 4; ++m) _Pragma("unroll") for (int n = 0; n < 2; ++n) _Pragma("unroll") for (int k = 0; k < 2; ++k) \
;         acc[ai][bj][m][n] = __builtin_amdgcn_mfma_f32_16x16x32_bf16(Bt[n][k], At[m][k], acc[ai][bj][m][n], 0, 0, 0); __builtin_amdgcn_s_setprio(0); } while (0)
; #define PG8_WAIT_V(n) asm volatile("s_waitcnt vmcnt(" #n ")" ::: "memory")
; #define PG8_WAIT_L(n) asm volatile("s_waitcnt lgkmcnt(" #n ")" ::: "memory")
; #define PG8_BAR __builtin_amdgcn_s_barrier()
; #define PG8_SCHED __builtin_amdgcn_sched_barrier(0)
; template <class Epi, class Sched, bool ALIGN_EPI = false, bool SP2 = false>
; __device__ __forceinline__ void gemm_phase(LAS unsigned char* lds, const Gemm g, const Sched& S, const Epi& E, int wid) {
;     ...
;             PG8_WAIT_V(8); PG8_WAIT_L(0); PG8_BAR; PG8_MMA(0, 0, At, B0); PG8_MMA(0, 1, At, B1); PG8_BAR; PG8_SCHED;
;             PG8_LDA(At, 1, 1); PG8_STAGE(PG8_SB(1, 0), b3, voffB); PG8_STAGE(PG8_SB(1, 1), b3 + hstepB, voffB); PG8_STAGE(PG8_SA(1, 0), a3, voffA);
;             PG8_WAIT_V(8); PG8_WAIT_L(0); PG8_BAR; PG8_MMA(1, 0, At, B0); PG8_MMA(1, 1, At, B1); PG8_BAR; PG8_SCHED;
	s_setprio 1
	s_waitcnt lgkmcnt(0)
	v_mfma_f32_16x16x32_bf16 v[124:127], v[128:131], v[170:173], v[124:127]
	v_mfma_f32_16x16x32_bf16 v[120:123], v[136:139], v[170:173], v[120:123]
	v_mfma_f32_16x16x32_bf16 v[108:111], v[128:131], v[178:181], v[108:111]
	v_mfma_f32_16x16x32_bf16 v[104:107], v[136:139], v[178:181], v[104:107]
	v_mfma_f32_16x16x32_bf16 v[92:95], v[128:131], v[200:203], v[92:95]
	v_mfma_f32_16x16x32_bf16 v[88:91], v[136:139], v[200:203], v[88:91]
	v_mfma_f32_16x16x32_bf16 v[76:79], v[128:131], v[208:211], v[76:79]
	v_mfma_f32_16x16x32_bf16 v[72:75], v[136:139], v[208:211], v[72:75]
	v_mfma_f32_16x16x32_bf16 v[124:127], v[132:135], v[174:177], v[124:127]
	v_mfma_f32_16x16x32_bf16 v[120:123], v[140:143], v[174:177], v[120:123]
	v_mfma_f32_16x16x32_bf16 v[108:111], v[132:135], v[186:189], v[108:111]
	v_mfma_f32_16x16x32_bf16 v[104:107], v[140:143], v[186:189], v[104:107]
	v_mfma_f32_16x16x32_bf16 v[92:95], v[132:135], v[204:207], v[92:95]
	v_mfma_f32_16x16x32_bf16 v[88:91], v[140:143], v[204:207], v[88:91]
	v_mfma_f32_16x16x32_bf16 v[76:79], v[132:135], v[212:215], v[76:79]
	v_mfma_f32_16x16x32_bf16 v[72:75], v[140:143], v[212:215], v[72:75]
	s_setprio 0
	s_setprio 1
	v_mfma_f32_16x16x32_bf16 v[116:119], v[144:147], v[170:173], v[116:119]
	v_mfma_f32_16x16x32_bf16 v[112:115], v[152:155], v[170:173], v[112:115]
	v_mfma_f32_16x16x32_bf16 v[100:103], v[144:147], v[178:181], v[100:103]
	v_mfma_f32_16x16x32_bf16 v[96:99], v[152:155], v[178:181], v[96:99]
	v_mfma_f32_16x16x32_bf16 v[84:87], v[144:147], v[200:203], v[84:87]
	v_mfma_f32_16x16x32_bf16 v[80:83], v[152:155], v[200:203], v[80:83]
	v_mfma_f32_16x16x32_bf16 v[68:71], v[144:147], v[208:211], v[68:71]
	v_mfma_f32_16x16x32_bf16 v[64:67], v[152:155], v[208:211], v[64:67]
	v_mfma_f32_16x16x32_bf16 v[116:119], v[148:151], v[174:177], v[116:119]
	v_mfma_f32_16x16x32_bf16 v[112:115], v[166:169], v[174:177], v[112:115]
	v_mfma_f32_16x16x32_bf16 v[100:103], v[148:151], v[186:189], v[100:103]
	v_mfma_f32_16x16x32_bf16 v[96:99], v[166:169], v[186:189], v[96:99]
	v_mfma_f32_16x16x32_bf16 v[84:87], v[148:151], v[204:207], v[84:87]
	v_mfma_f32_16x16x32_bf16 v[80:83], v[166:169], v[204:207], v[80:83]
	v_mfma_f32_16x16x32_bf16 v[68:71], v[148:151], v[212:215], v[68:71]
	v_mfma_f32_16x16x32_bf16 v[64:67], v[166:169], v[212:215], v[64:67]
	s_setprio 0
	s_barrier
	s_add_i32 s38, s59, s27
	v_lshl_add_u64 v[190:191], v[190:191], 0, s[64:65]
	s_mov_b32 m0, s38
	ds_read_b128 v[170:173], v185 offset:49152
	ds_read_b128 v[174:177], v185 offset:50176
	ds_read_b128 v[178:181], v185 offset:51200
	ds_read_b128 v[186:189], v185 offset:52224
	ds_read_b128 v[200:203], v185 offset:53248
	ds_read_b128 v[204:207], v185 offset:54272
	ds_read_b128 v[208:211], v185 offset:55296
	ds_read_b128 v[212:215], v185 offset:56320
	global_load_lds_dwordx4 v[190:191], off
	s_add_i32 m0, s38, 0x2000
	s_add_u32 s38, s44, 0x160080
	v_lshl_add_u64 v[190:191], v[216:217], 0, s[64:65]
	s_addc_u32 s39, s45, 0
	s_add_i32 s44, s60, s27
	global_load_lds_dwordx4 v[190:191], off
	v_lshl_add_u64 v[190:191], s[38:39], 0, v[192:193]
	s_mov_b32 m0, s44
	s_nop 0
	global_load_lds_dwordx4 v[190:191], off
	v_lshl_add_u64 v[190:191], s[38:39], 0, v[156:157]
	s_add_i32 m0, s44, 0x2000
	s_nop 0
	global_load_lds_dwordx4 v[190:191], off
	v_lshl_add_u64 v[190:191], v[218:219], 0, s[64:65]
	s_mov_b32 m0, s50
	s_nop 0
	global_load_lds_dwordx4 v[190:191], off
	v_lshl_add_u64 v[190:191], v[228:229], 0, s[64:65]
	s_mov_b32 m0, s51
	s_nop 0
	global_load_lds_dwordx4 v[190:191], off
	s_waitcnt vmcnt(8)
	s_waitcnt lgkmcnt(0)
	s_barrier
	s_setprio 1
	s_waitcnt lgkmcnt(0)
	v_mfma_f32_16x16x32_bf16 v[60:63], v[128:131], v[170:173], v[60:63]
	v_mfma_f32_16x16x32_bf16 v[56:59], v[136:139], v[170:173], v[56:59]
	v_mfma_f32_16x16x32_bf16 v[44:47], v[128:131], v[178:181], v[44:47]
	v_mfma_f32_16x16x32_bf16 v[40:43], v[136:139], v[178:181], v[40:43]
	v_mfma_f32_16x16x32_bf16 v[28:31], v[128:131], v[200:203], v[28:31]
	v_mfma_f32_16x16x32_bf16 v[24:27], v[136:139], v[200:203], v[24:27]
	v_mfma_f32_16x16x32_bf16 v[12:15], v[128:131], v[208:211], v[12:15]
	v_mfma_f32_16x16x32_bf16 v[8:11], v[136:139], v[208:211], v[8:11]
	v_mfma_f32_16x16x32_bf16 v[60:63], v[132:135], v[174:177], v[60:63]
	v_mfma_f32_16x16x32_bf16 v[56:59], v[140:143], v[174:177], v[56:59]
	v_mfma_f32_16x16x32_bf16 v[44:47], v[132:135], v[186:189], v[44:47]
	v_mfma_f32_16x16x32_bf16 v[40:43], v[140:143], v[186:189], v[40:43]
	v_mfma_f32_16x16x32_bf16 v[28:31], v[132:135], v[204:207], v[28:31]
	v_mfma_f32_16x16x32_bf16 v[24:27], v[140:143], v[204:207], v[24:27]
	v_mfma_f32_16x16x32_bf16 v[12:15], v[132:135], v[212:215], v[12:15]
	v_mfma_f32_16x16x32_bf16 v[8:11], v[140:143], v[212:215], v[8:11]
	s_setprio 0
	s_setprio 1
	v_mfma_f32_16x16x32_bf16 v[52:55], v[144:147], v[170:173], v[52:55]
	v_mfma_f32_16x16x32_bf16 v[48:51], v[152:155], v[170:173], v[48:51]
	v_mfma_f32_16x16x32_bf16 v[36:39], v[144:147], v[178:181], v[36:39]
	v_mfma_f32_16x16x32_bf16 v[32:35], v[152:155], v[178:181], v[32:35]
	v_mfma_f32_16x16x32_bf16 v[20:23], v[144:147], v[200:203], v[20:23]
	v_mfma_f32_16x16x32_bf16 v[16:19], v[152:155], v[200:203], v[16:19]
	v_mfma_f32_16x16x32_bf16 v[4:7], v[144:147], v[208:211], v[4:7]
	v_mfma_f32_16x16x32_bf16 v[0:3], v[152:155], v[208:211], v[0:3]
	v_mfma_f32_16x16x32_bf16 v[52:55], v[148:151], v[174:177], v[52:55]
	v_mfma_f32_16x16x32_bf16 v[48:51], v[166:169], v[174:177], v[48:51]
	v_mfma_f32_16x16x32_bf16 v[36:39], v[148:151], v[186:189], v[36:39]
	v_mfma_f32_16x16x32_bf16 v[32:35], v[166:169], v[186:189], v[32:35]
	v_mfma_f32_16x16x32_bf16 v[20:23], v[148:151], v[204:207], v[20:23]
	v_mfma_f32_16x16x32_bf16 v[16:19], v[166:169], v[204:207], v[16:19]
	v_mfma_f32_16x16x32_bf16 v[4:7], v[148:151], v[212:215], v[4:7]
	v_mfma_f32_16x16x32_bf16 v[0:3], v[166:169], v[212:215], v[0:3]
	s_setprio 0
	s_barrier
	s_add_i32 s58, s58, 2
	s_add_u32 s56, s56, 0x100
	s_addc_u32 s57, s57, 0
	s_cmpk_gt_u32 s58, 0x55
	s_mov_b64 s[38:39], s[40:41]
	s_cbranch_scc0 .LBB0_1151
	s_and_b64 vcc, exec, s[30:31]
	s_cbranch_vccz .LBB0_1154
	s_barrier
